# F1 SwiGLU epilogue: 25 adjacent pairs of +1.0 adds packed into v_pk_add_f32 (strategy 7, packed VALU in a VALU-bound epilogue)
# baseline (speedup 1.0000x reference)
.LBB0_786:
	v_exp_f32_e32 v144, v122
	v_exp_f32_e32 v145, v123
	v_pk_mul_f32 v[122:123], v[122:123], v[126:127]
	v_exp_f32_e32 v126, v114
	v_exp_f32_e32 v127, v115
	v_pk_mul_f32 v[120:121], v[116:117], v[120:121]
	v_exp_f32_e32 v116, v116
	v_exp_f32_e32 v117, v117
	v_pk_add_f32 v[126:127], v[126:127], 1.0 op_sel_hi:[1,0]
	v_rcp_f32_e32 v126, v126
	v_rcp_f32_e32 v127, v127
	v_pk_add_f32 v[116:117], v[116:117], 1.0 op_sel_hi:[1,0]
	v_pk_mul_f32 v[128:129], v[124:125], v[128:129]
	v_exp_f32_e32 v124, v124
	v_exp_f32_e32 v125, v125
	v_rcp_f32_e32 v116, v116
	v_rcp_f32_e32 v117, v117
	s_ashr_i32 s25, s24, 31
	v_pk_mul_f32 v[114:115], v[114:115], v[118:119]
	v_readlane_b32 s4, v254, 2
	s_lshl_b64 s[2:3], s[24:25], 8
	v_pk_mul_f32 v[114:115], v[126:127], v[114:115]
	v_readlane_b32 s5, v254, 3
	v_lshl_add_u64 v[142:143], v[134:135], 0, s[2:3]
	v_cvt_pk_bf16_f32 v118, v114, v115
	v_mov_b64_e32 v[114:115], s[4:5]
	s_movk_i32 s15, 0x1600
	v_pk_add_f32 v[144:145], v[144:145], 1.0 op_sel_hi:[1,0]
	v_pk_add_f32 v[124:125], v[124:125], 1.0 op_sel_hi:[1,0]
	v_pk_mul_f32 v[120:121], v[116:117], v[120:121]
	v_mad_u64_u32 v[114:115], s[4:5], v142, s15, v[114:115]
	v_rcp_f32_e32 v144, v144
	v_rcp_f32_e32 v145, v145
	v_rcp_f32_e32 v124, v124
	v_rcp_f32_e32 v125, v125
	v_cvt_pk_bf16_f32 v119, v120, v121
	v_mov_b32_e32 v120, v115
	s_lshl_b32 s2, s22, 7
	v_mad_u64_u32 v[120:121], s[4:5], v143, s15, v[120:121]
	s_ashr_i32 s3, s2, 31
	v_mov_b32_e32 v115, v120
	v_lshl_add_u64 v[114:115], s[2:3], 1, v[114:115]
	v_pk_mul_f32 v[122:123], v[144:145], v[122:123]
	v_pk_mul_f32 v[124:125], v[124:125], v[128:129]
	v_lshl_add_u64 v[114:115], v[114:115], 0, s[68:69]
	v_cvt_pk_bf16_f32 v116, v122, v123
	v_cvt_pk_bf16_f32 v117, v124, v125
	v_lshl_add_u64 v[114:115], v[114:115], 0, v[0:1]
	global_store_dwordx4 v[114:115], v[116:119], off
	v_pk_mul_f32 v[112:113], v[108:109], v[112:113]
	v_exp_f32_e32 v108, v108
	v_exp_f32_e32 v116, v106
	v_exp_f32_e32 v117, v107
	v_pk_mul_f32 v[106:107], v[106:107], v[110:111]
	v_exp_f32_e32 v110, v98
	v_exp_f32_e32 v111, v99
	v_pk_mul_f32 v[98:99], v[98:99], v[102:103]
	v_exp_f32_e32 v109, v109
	v_pk_add_f32 v[110:111], v[110:111], 1.0 op_sel_hi:[1,0]
	v_rcp_f32_e32 v110, v110
	v_rcp_f32_e32 v111, v111
	v_pk_add_f32 v[116:117], v[116:117], 1.0 op_sel_hi:[1,0]
	v_add_f32_e32 v108, 1.0, v108
	v_pk_mul_f32 v[102:103], v[110:111], v[98:99]
	v_exp_f32_e32 v98, v100
	v_exp_f32_e32 v99, v101
	v_add_f32_e32 v109, 1.0, v109
	v_rcp_f32_e32 v116, v116
	v_pk_add_f32 v[98:99], v[98:99], 1.0 op_sel_hi:[1,0]
	v_rcp_f32_e32 v117, v117
	v_rcp_f32_e32 v108, v108
	v_rcp_f32_e32 v109, v109
	v_rcp_f32_e32 v98, v98
	v_rcp_f32_e32 v99, v99
	v_pk_mul_f32 v[104:105], v[100:101], v[104:105]
	s_mov_b32 s2, 0x16000
	v_pk_mul_f32 v[106:107], v[116:117], v[106:107]
	v_pk_mul_f32 v[108:109], v[108:109], v[112:113]
	v_pk_mul_f32 v[104:105], v[98:99], v[104:105]
	v_cvt_pk_bf16_f32 v100, v102, v103
	v_add_co_u32_e32 v102, vcc, s2, v114
	v_cvt_pk_bf16_f32 v98, v106, v107
	v_cvt_pk_bf16_f32 v99, v108, v109
	v_cvt_pk_bf16_f32 v101, v104, v105
	v_addc_co_u32_e32 v103, vcc, 0, v115, vcc
	global_store_dwordx4 v[102:103], v[98:101], off
	v_pk_mul_f32 v[96:97], v[92:93], v[96:97]
	v_exp_f32_e32 v92, v92
	v_exp_f32_e32 v98, v90
	v_exp_f32_e32 v99, v91
	v_pk_mul_f32 v[90:91], v[90:91], v[94:95]
	v_exp_f32_e32 v94, v82
	v_exp_f32_e32 v95, v83
	v_pk_mul_f32 v[82:83], v[82:83], v[86:87]
	v_exp_f32_e32 v93, v93
	v_pk_add_f32 v[94:95], v[94:95], 1.0 op_sel_hi:[1,0]
	v_rcp_f32_e32 v94, v94
	v_rcp_f32_e32 v95, v95
	v_pk_add_f32 v[98:99], v[98:99], 1.0 op_sel_hi:[1,0]
	v_add_f32_e32 v92, 1.0, v92
	v_pk_mul_f32 v[86:87], v[94:95], v[82:83]
	v_exp_f32_e32 v82, v84
	v_exp_f32_e32 v83, v85
	v_add_f32_e32 v93, 1.0, v93
	v_rcp_f32_e32 v98, v98
	v_pk_add_f32 v[82:83], v[82:83], 1.0 op_sel_hi:[1,0]
	v_rcp_f32_e32 v99, v99
	v_rcp_f32_e32 v92, v92
	v_rcp_f32_e32 v93, v93
	v_rcp_f32_e32 v82, v82
	v_rcp_f32_e32 v83, v83
	v_pk_mul_f32 v[88:89], v[84:85], v[88:89]
	s_mov_b32 s2, 0x2c000
	v_pk_mul_f32 v[90:91], v[98:99], v[90:91]
	v_pk_mul_f32 v[92:93], v[92:93], v[96:97]
	v_pk_mul_f32 v[88:89], v[82:83], v[88:89]
	v_cvt_pk_bf16_f32 v84, v86, v87
	v_add_co_u32_e32 v86, vcc, s2, v114
	v_cvt_pk_bf16_f32 v82, v90, v91
	v_cvt_pk_bf16_f32 v83, v92, v93
	v_cvt_pk_bf16_f32 v85, v88, v89
	v_addc_co_u32_e32 v87, vcc, 0, v115, vcc
	global_store_dwordx4 v[86:87], v[82:85], off
	v_pk_mul_f32 v[80:81], v[76:77], v[80:81]
	v_exp_f32_e32 v76, v76
	v_exp_f32_e32 v82, v74
	v_exp_f32_e32 v83, v75
	v_pk_mul_f32 v[74:75], v[74:75], v[78:79]
	v_exp_f32_e32 v78, v66
	v_exp_f32_e32 v79, v67
	v_pk_mul_f32 v[66:67], v[66:67], v[70:71]
	v_exp_f32_e32 v77, v77
	v_pk_add_f32 v[78:79], v[78:79], 1.0 op_sel_hi:[1,0]
	v_rcp_f32_e32 v78, v78
	v_rcp_f32_e32 v79, v79
	v_pk_add_f32 v[82:83], v[82:83], 1.0 op_sel_hi:[1,0]
	v_add_f32_e32 v76, 1.0, v76
	v_pk_mul_f32 v[70:71], v[78:79], v[66:67]
	v_exp_f32_e32 v66, v68
	v_exp_f32_e32 v67, v69
	v_add_f32_e32 v77, 1.0, v77
	v_rcp_f32_e32 v82, v82
	v_pk_add_f32 v[66:67], v[66:67], 1.0 op_sel_hi:[1,0]
	v_rcp_f32_e32 v83, v83
	v_rcp_f32_e32 v76, v76
	v_rcp_f32_e32 v77, v77
	v_rcp_f32_e32 v66, v66
	v_rcp_f32_e32 v67, v67
	v_pk_mul_f32 v[72:73], v[68:69], v[72:73]
	s_mov_b32 s2, 0x42000
	v_pk_mul_f32 v[74:75], v[82:83], v[74:75]
	v_pk_mul_f32 v[76:77], v[76:77], v[80:81]
	v_pk_mul_f32 v[72:73], v[66:67], v[72:73]
	v_cvt_pk_bf16_f32 v68, v70, v71
	v_add_co_u32_e32 v70, vcc, s2, v114
	v_cvt_pk_bf16_f32 v66, v74, v75
	v_cvt_pk_bf16_f32 v67, v76, v77
	v_cvt_pk_bf16_f32 v69, v72, v73
	v_addc_co_u32_e32 v71, vcc, 0, v115, vcc
	global_store_dwordx4 v[70:71], v[66:69], off
	v_pk_mul_f32 v[64:65], v[60:61], v[64:65]
	v_exp_f32_e32 v60, v60
	v_exp_f32_e32 v66, v58
	v_exp_f32_e32 v67, v59
	v_pk_mul_f32 v[58:59], v[58:59], v[62:63]
	v_exp_f32_e32 v62, v50
	v_exp_f32_e32 v63, v51
	v_pk_mul_f32 v[50:51], v[50:51], v[54:55]
	v_exp_f32_e32 v61, v61
	v_pk_add_f32 v[62:63], v[62:63], 1.0 op_sel_hi:[1,0]
	v_rcp_f32_e32 v62, v62
	v_rcp_f32_e32 v63, v63
	v_pk_add_f32 v[66:67], v[66:67], 1.0 op_sel_hi:[1,0]
	v_add_f32_e32 v60, 1.0, v60
	v_pk_mul_f32 v[54:55], v[62:63], v[50:51]
	v_exp_f32_e32 v50, v52
	v_exp_f32_e32 v51, v53
	v_add_f32_e32 v61, 1.0, v61
	v_rcp_f32_e32 v66, v66
	v_pk_add_f32 v[50:51], v[50:51], 1.0 op_sel_hi:[1,0]
	v_rcp_f32_e32 v67, v67
	v_rcp_f32_e32 v60, v60
	v_rcp_f32_e32 v61, v61
	v_rcp_f32_e32 v50, v50
	v_rcp_f32_e32 v51, v51
	v_pk_mul_f32 v[56:57], v[52:53], v[56:57]
	s_mov_b32 s2, 0xb0000
	v_pk_mul_f32 v[58:59], v[66:67], v[58:59]
	v_pk_mul_f32 v[60:61], v[60:61], v[64:65]
	v_pk_mul_f32 v[56:57], v[50:51], v[56:57]
	v_cvt_pk_bf16_f32 v52, v54, v55
	v_add_co_u32_e32 v54, vcc, s2, v114
	v_cvt_pk_bf16_f32 v50, v58, v59
	v_cvt_pk_bf16_f32 v51, v60, v61
	v_cvt_pk_bf16_f32 v53, v56, v57
	v_addc_co_u32_e32 v55, vcc, 0, v115, vcc
	global_store_dwordx4 v[54:55], v[50:53], off
	v_pk_mul_f32 v[48:49], v[44:45], v[48:49]
	v_exp_f32_e32 v44, v44
	v_exp_f32_e32 v50, v42
	v_exp_f32_e32 v51, v43
	v_pk_mul_f32 v[42:43], v[42:43], v[46:47]
	v_exp_f32_e32 v46, v34
	v_exp_f32_e32 v47, v35
	v_pk_mul_f32 v[34:35], v[34:35], v[38:39]
	v_exp_f32_e32 v45, v45
	v_pk_add_f32 v[46:47], v[46:47], 1.0 op_sel_hi:[1,0]
	v_rcp_f32_e32 v46, v46
	v_rcp_f32_e32 v47, v47
	v_pk_add_f32 v[50:51], v[50:51], 1.0 op_sel_hi:[1,0]
	v_add_f32_e32 v44, 1.0, v44
	v_pk_mul_f32 v[38:39], v[46:47], v[34:35]
	v_exp_f32_e32 v34, v36
	v_exp_f32_e32 v35, v37
	v_add_f32_e32 v45, 1.0, v45
	v_rcp_f32_e32 v50, v50
	v_pk_add_f32 v[34:35], v[34:35], 1.0 op_sel_hi:[1,0]
	v_rcp_f32_e32 v51, v51
	v_rcp_f32_e32 v44, v44
	v_rcp_f32_e32 v45, v45
	v_rcp_f32_e32 v34, v34
	v_rcp_f32_e32 v35, v35
	v_pk_mul_f32 v[40:41], v[36:37], v[40:41]
	s_mov_b32 s2, 0xc6000
	v_pk_mul_f32 v[42:43], v[50:51], v[42:43]
	v_pk_mul_f32 v[44:45], v[44:45], v[48:49]
	v_pk_mul_f32 v[40:41], v[34:35], v[40:41]
	v_cvt_pk_bf16_f32 v36, v38, v39
	v_add_co_u32_e32 v38, vcc, s2, v114
	v_cvt_pk_bf16_f32 v34, v42, v43
	v_cvt_pk_bf16_f32 v35, v44, v45
	v_cvt_pk_bf16_f32 v37, v40, v41
	v_addc_co_u32_e32 v39, vcc, 0, v115, vcc
	global_store_dwordx4 v[38:39], v[34:37], off
	v_pk_mul_f32 v[32:33], v[28:29], v[32:33]
	v_exp_f32_e32 v28, v28
	v_exp_f32_e32 v34, v26
	v_exp_f32_e32 v35, v27
	v_pk_mul_f32 v[26:27], v[26:27], v[30:31]
	v_exp_f32_e32 v30, v18
	v_exp_f32_e32 v31, v19
	v_pk_mul_f32 v[18:19], v[18:19], v[22:23]
	v_exp_f32_e32 v29, v29
	v_pk_add_f32 v[30:31], v[30:31], 1.0 op_sel_hi:[1,0]
	v_rcp_f32_e32 v30, v30
	v_rcp_f32_e32 v31, v31
	v_pk_add_f32 v[34:35], v[34:35], 1.0 op_sel_hi:[1,0]
	v_add_f32_e32 v28, 1.0, v28
	v_pk_mul_f32 v[22:23], v[30:31], v[18:19]
	v_exp_f32_e32 v18, v20
	v_exp_f32_e32 v19, v21
	v_add_f32_e32 v29, 1.0, v29
	v_rcp_f32_e32 v34, v34
	v_pk_add_f32 v[18:19], v[18:19], 1.0 op_sel_hi:[1,0]
	v_rcp_f32_e32 v35, v35
	v_rcp_f32_e32 v28, v28
	v_rcp_f32_e32 v29, v29
	v_rcp_f32_e32 v18, v18
	v_rcp_f32_e32 v19, v19
	v_pk_mul_f32 v[24:25], v[20:21], v[24:25]
	s_mov_b32 s2, 0xdc000
	v_pk_mul_f32 v[26:27], v[34:35], v[26:27]
	v_pk_mul_f32 v[28:29], v[28:29], v[32:33]
	v_pk_mul_f32 v[24:25], v[18:19], v[24:25]
	v_cvt_pk_bf16_f32 v20, v22, v23
	v_add_co_u32_e32 v22, vcc, s2, v114
	v_cvt_pk_bf16_f32 v18, v26, v27
	v_cvt_pk_bf16_f32 v19, v28, v29
	v_cvt_pk_bf16_f32 v21, v24, v25
	v_addc_co_u32_e32 v23, vcc, 0, v115, vcc
	global_store_dwordx4 v[22:23], v[18:21], off
	v_pk_mul_f32 v[16:17], v[12:13], v[16:17]
	v_exp_f32_e32 v12, v12
	v_exp_f32_e32 v18, v10
	v_exp_f32_e32 v19, v11
	v_pk_mul_f32 v[10:11], v[10:11], v[14:15]
	v_exp_f32_e32 v14, v2
	v_exp_f32_e32 v15, v3
	v_pk_mul_f32 v[2:3], v[2:3], v[6:7]
	v_exp_f32_e32 v13, v13
	v_pk_add_f32 v[14:15], v[14:15], 1.0 op_sel_hi:[1,0]
	v_rcp_f32_e32 v14, v14
	v_rcp_f32_e32 v15, v15
	v_pk_add_f32 v[18:19], v[18:19], 1.0 op_sel_hi:[1,0]
	v_add_f32_e32 v12, 1.0, v12
	v_pk_mul_f32 v[6:7], v[14:15], v[2:3]
	v_exp_f32_e32 v2, v4
	v_exp_f32_e32 v3, v5
	v_add_f32_e32 v13, 1.0, v13
	v_rcp_f32_e32 v18, v18
	v_pk_add_f32 v[2:3], v[2:3], 1.0 op_sel_hi:[1,0]
	v_rcp_f32_e32 v19, v19
	v_rcp_f32_e32 v12, v12
	v_rcp_f32_e32 v13, v13
	v_rcp_f32_e32 v2, v2
	v_rcp_f32_e32 v3, v3
	v_pk_mul_f32 v[8:9], v[4:5], v[8:9]
	v_cvt_pk_bf16_f32 v4, v6, v7
	v_add_co_u32_e32 v6, vcc, 0xf2000, v114
	v_pk_mul_f32 v[10:11], v[18:19], v[10:11]
	v_pk_mul_f32 v[12:13], v[12:13], v[16:17]
	v_pk_mul_f32 v[8:9], v[2:3], v[8:9]
	v_addc_co_u32_e32 v7, vcc, 0, v115, vcc
	v_cvt_pk_bf16_f32 v2, v10, v11
	v_cvt_pk_bf16_f32 v3, v12, v13
	v_cvt_pk_bf16_f32 v5, v8, v9
	s_mov_b64 s[2:3], -1
	s_andn2_b64 vcc, exec, s[0:1]
	global_store_dwordx4 v[6:7], v[2:5], off
	s_cbranch_vccnz .LBB0_779
	s_andn2_b64 vcc, exec, s[10:11]
	s_cbranch_vccnz .LBB0_778
	s_barrier
	s_branch .LBB0_778
